# MLA attention loop: next K/V/KR tiles loaded HBM->LDS directly (global_load_lds_dwordx4, source-side permutation), no register staging or ds_write block
# baseline (speedup 1.0000x reference)
; #define LAS __attribute__((address_space(3)))
; __device__ __forceinline__ int v_st(int k, int c) { const int kk = (k & ~0xC) | ((k & 4) << 1) | ((k & 8) >> 1); return ((kk >> 3) * 4 + (c >> 5)) * 512 + ((kk & 7) * 32 + (c & 31)) * 2; }
; __device__ __forceinline__ int v_rd_base(int lane) { return ((lane & 3) << 3) | (((lane >> 2) & 3) << 6) | (((lane >> 4) & 1) << 5) | (((lane >> 5) & 1) << 8); }
; template <int KIND>
; __device__ __forceinline__ void run_unit(LAS char* lds, const UnitArgs& U, int tid_in) {
;     ...
;     const int wid = __builtin_amdgcn_readfirstlane(tid >> 6), lane = tid & 63, r32 = lane & 31, hi = lane >> 5;
;     const int sr = tid >> 4, sc = (tid & 15) * 8;
;     const int qlo = U.P0 + wid * 32, rowpos = qlo + r32;
;     const float sc_ = MLA ? SC192 : SC128; const float C2 = 1.4426950408889634f * sc_;
;     LAS float* wsf = (LAS float*)(lds + OFF_WS) + wid * 96; LAS float* li_l = wsf; LAS float* al_l = wsf + 32; LAS float* g_l = wsf + 64;
;     half8 qr[MLA ? 12 : 8];
;     { const h16* qp = U.Q + (size_t)(wid * 32 + r32) * U.qld + hi * 8;
; #pragma unroll
;       for (int d0 = 0; d0 < (MLA ? 12 : 8); ++d0) qr[d0] = *(const half8*)(qp + d0 * 16); }
;     unsigned mb0 = 0, mb1 = 0, mb2 = 0, mb3 = 0;
;     if constexpr (KIND == K_MOBA) { const int* s = (const int*)U.mk + (size_t)rowpos * 16;
; #pragma unroll
;         for (int i = 0; i < 3; ++i) { const int b = s[i]; if (b >= 0) mb0 |= 1u << b; } }
;     if constexpr (KIND == K_SLC) { const u32x4 m = *(const u32x4*)((const unsigned*)U.mk + (size_t)rowpos * 4); mb0 = m[0]; mb1 = m[1]; mb2 = m[2]; mb3 = m[3]; }
;     const int nvis_row = rowpos >= 31 ? ((rowpos - 31) >> 4) + 1 : 0;
;     const int NT = U.j_hi - U.j_lo;
;     half8 st_k0, st_k1, st_v0, st_v1, st_kr; unsigned dm_lo = 0, dm_hi = 0, dn_lo = 0, dn_hi = 0;
;     const int kws = FA_KSWZ(sr, sc * 2), vst0 = v_st(sr, sc), vst1 = v_st(32 + sr, sc), krw = FA_KRSWZ(tid >> 3, (tid & 7) * 16);
;     const int vb0 = (int)(unsigned)(size_t)(lds + OFF_V) + v_rd_base(lane);
;     ...
;     float m_reg = -1e30f, l_reg = 0.f; f32x16 o[4];
; #pragma unroll
;     for (int d = 0; d < 4; ++d)
; #pragma unroll
;         for (int r = 0; r < 16; ++r) o[d][r] = 0.f;
;     FA_LOADT(U.j_lo); asm volatile("s_waitcnt vmcnt(0)" ::: "memory"); FA_WRITET(0); dm_lo = dn_lo; dm_hi = dn_hi;
.LBB0_4968:
	s_andn2_b64 vcc, exec, s[0:1]
	s_cbranch_vccnz .LBB0_4921
	s_cmp_eq_u32 s10, 1
	s_mov_b64 s[0:1], -1
	s_cbranch_scc1 .LBB0_4987
	s_lshl_b32 s0, s14, 13
	s_add_i32 s0, s0, s2
	s_mul_hi_u32 s1, s0, 0x180
	s_mulk_i32 s0, 0x180
	v_readlane_b32 s6, v252, 30
	s_add_u32 s0, s6, s0
	v_readlane_b32 s6, v252, 31
	s_addc_u32 s1, s6, s1
	s_lshl_b32 s8, s14, 21
	v_readlane_b32 s6, v252, 24
	v_mov_b32_e32 v1, v0
	s_add_u32 s6, s6, s8
	v_readlane_b32 s7, v252, 25
	s_addc_u32 s7, s7, 0
	s_waitcnt vmcnt(10)
	v_ashrrev_i32_e32 v182, 4, v1
	v_readlane_b32 s9, v252, 26
	v_lshlrev_b32_e32 v18, 3, v1
	v_add_u32_e32 v6, 32, v182
	v_ashrrev_i32_e32 v183, 31, v182
	s_add_u32 s8, s9, s8
	v_readlane_b32 s9, v252, 27
	v_and_b32_e32 v2, 0x78, v18
	v_lshlrev_b64 v[10:11], 8, v[182:183]
	v_ashrrev_i32_e32 v7, 31, v6
	s_addc_u32 s9, s9, 0
	v_lshlrev_b32_e32 v4, 1, v2
	v_lshl_add_u64 v[12:13], s[6:7], 0, v[10:11]
	v_mov_b32_e32 v5, v3
	v_lshlrev_b64 v[14:15], 8, v[6:7]
	v_ashrrev_i32_e32 v8, 3, v1
	v_lshl_add_u64 v[12:13], v[12:13], 0, v[4:5]
	v_lshl_add_u64 v[16:17], s[6:7], 0, v[14:15]
	v_lshl_add_u64 v[10:11], s[8:9], 0, v[10:11]
	v_lshl_add_u64 v[16:17], v[16:17], 0, v[4:5]
	global_load_dwordx4 v[114:117], v[12:13], off
	global_load_dwordx4 v[118:121], v[16:17], off
	v_lshl_add_u64 v[10:11], v[10:11], 0, v[4:5]
	v_lshl_add_u64 v[12:13], s[8:9], 0, v[14:15]
	v_ashrrev_i32_e32 v9, 31, v8
	v_readlane_b32 s24, v252, 10
	v_lshl_add_u64 v[12:13], v[12:13], 0, v[4:5]
	global_load_dwordx4 v[122:125], v[10:11], off
	global_load_dwordx4 v[126:129], v[12:13], off
	v_lshlrev_b64 v[10:11], 7, v[8:9]
	v_readlane_b32 s25, v252, 11
	s_waitcnt vmcnt(12)
	v_lshlrev_b32_e32 v190, 4, v1
	v_readfirstlane_b32 s10, v1
	v_lshl_add_u64 v[10:11], s[24:25], 0, v[10:11]
	v_and_b32_e32 v12, 0x70, v190
	v_mov_b32_e32 v13, v3
	s_ashr_i32 s10, s10, 6
	v_lshl_add_u64 v[10:11], v[10:11], 0, v[12:13]
	v_and_b32_e32 v191, 31, v1
	s_lshl_b32 s11, s10, 5
	global_load_dwordx4 v[178:181], v[10:11], off
	v_bfe_u32 v183, v1, 5, 1
	v_or_b32_e32 v2, s11, v191
	v_mov_b64_e32 v[10:11], s[0:1]
	s_movk_i32 s0, 0x180
	v_mad_i64_i32 v[10:11], s[0:1], v2, s0, v[10:11]
	v_lshlrev_b32_e32 v2, 4, v183
	v_lshl_add_u64 v[10:11], v[10:11], 0, v[2:3]
	global_load_dwordx4 v[130:133], v[10:11], off
	global_load_dwordx4 v[134:137], v[10:11], off offset:32
	global_load_dwordx4 v[138:141], v[10:11], off offset:64
	global_load_dwordx4 v[142:145], v[10:11], off offset:96
	global_load_dwordx4 v[146:149], v[10:11], off offset:128
	global_load_dwordx4 v[150:153], v[10:11], off offset:160
	global_load_dwordx4 v[154:157], v[10:11], off offset:192
	global_load_dwordx4 v[158:161], v[10:11], off offset:224
	global_load_dwordx4 v[162:165], v[10:11], off offset:256
	global_load_dwordx4 v[166:169], v[10:11], off offset:288
	global_load_dwordx4 v[170:173], v[10:11], off offset:320
	global_load_dwordx4 v[174:177], v[10:11], off offset:352
	v_and_b32_e32 v9, 0xfffff0, v182
	v_lshlrev_b32_e32 v10, 1, v182
	v_and_or_b32 v9, v10, 8, v9
	v_lshrrev_b32_e32 v10, 1, v182
	v_and_b32_e32 v14, 3, v182
	v_and_or_b32 v10, v10, 4, v14
	v_and_b32_e32 v14, 0xfffff0, v6
	v_lshlrev_b32_e32 v6, 1, v6
	v_lshrrev_b32_e32 v9, 1, v9
	v_bfe_u32 v11, v18, 5, 2
	v_and_or_b32 v6, v6, 8, v14
	v_or_b32_e32 v9, v9, v11
	v_lshrrev_b32_e32 v6, 1, v6
	v_lshlrev_b32_e32 v9, 9, v9
	v_lshlrev_b32_e32 v10, 6, v10
	v_or_b32_e32 v6, v6, v11
	v_xor_b32_e32 v11, v8, v1
	v_and_b32_e32 v15, 48, v4
	s_mul_i32 s17, s10, 0x180
	v_bitop3_b32 v7, v4, v1, s50 bitop3:0x78
	v_lshlrev_b32_e32 v6, 9, v6
	v_lshlrev_b32_e32 v11, 4, v11
	v_lshlrev_b32_e32 v14, 8, v182
	v_or3_b32 v204, v9, v10, v15
	v_and_b32_e32 v192, 63, v1
	s_add_i32 s17, s17, 0
	v_and_b32_e32 v11, 0x70, v11
	v_or3_b32 v205, v6, v10, v15
	v_lshlrev_b32_e32 v6, 7, v8
	v_add3_u32 v207, 0, v7, v14
	v_add_u32_e32 v7, 0, v204
	s_add_i32 s0, 0, 0x10000
	v_lshlrev_b32_e32 v1, 1, v1
	s_add_i32 s22, s17, 0x14000
	s_waitcnt vmcnt(0)
; __device__ __forceinline__ int v_st(int k, int c) { const int kk = (k & ~0xC) | ((k & 4) << 1) | ((k & 8) >> 1); return ((kk >> 3) * 4 + (c >> 5)) * 512 + ((kk & 7) * 32 + (c & 31)) * 2; }
; __device__ __forceinline__ int v_rd_base(int lane) { return ((lane & 3) << 3) | (((lane >> 2) & 3) << 6) | (((lane >> 4) & 1) << 5) | (((lane >> 5) & 1) << 8); }
; #define FA_WRITET(bf) do { *(LAS half8*)(lds + OFF_K + (bf) * SHM_K + kws) = st_k0; *(LAS half8*)(lds + OFF_K + (bf) * SHM_K + kws + 32 * 256) = st_k1; \
;         *(LAS half8*)(lds + OFF_V + (bf) * SHM_V + vst0) = st_v0; *(LAS half8*)(lds + OFF_V + (bf) * SHM_V + vst1) = st_v1; \
;         if constexpr (MLA) *(LAS half8*)(lds + OFF_KR + (bf) * SHM_KR + krw) = st_kr; } while (0)
; template <int KIND>
; __device__ __forceinline__ void run_unit(LAS char* lds, const UnitArgs& U, int tid_in) {
;     ...
;     const int kws = FA_KSWZ(sr, sc * 2), vst0 = v_st(sr, sc), vst1 = v_st(32 + sr, sc), krw = FA_KRSWZ(tid >> 3, (tid & 7) * 16);
;     const int vb0 = (int)(unsigned)(size_t)(lds + OFF_V) + v_rd_base(lane);
;     ...
;     float m_reg = -1e30f, l_reg = 0.f; f32x16 o[4];
; #pragma unroll
;     for (int d = 0; d < 4; ++d)
; #pragma unroll
;         for (int r = 0; r < 16; ++r) o[d][r] = 0.f;
;     FA_LOADT(U.j_lo); asm volatile("s_waitcnt vmcnt(0)" ::: "memory"); FA_WRITET(0); dm_lo = dn_lo; dm_hi = dn_hi;
	s_waitcnt vmcnt(16)
	ds_write_b128 v207, v[114:117] offset:32768
	s_waitcnt vmcnt(15)
	ds_write_b128 v207, v[118:121] offset:40960
	v_add3_u32 v208, s0, v11, v6
	v_and_b32_e32 v6, 32, v1
	v_lshl_add_u64 v[184:185], s[6:7], 0, v[4:5]
	s_movk_i32 s6, 0x118
	s_waitcnt vmcnt(14)
	ds_write_b128 v7, v[122:125]
	v_add_u32_e32 v7, 0, v205
	s_waitcnt vmcnt(13)
	ds_write_b128 v7, v[126:129]
	v_and_b32_e32 v7, 0xc0, v190
	v_bitop3_b32 v220, v2, v190, s50 bitop3:0x78
	v_bitop3_b32 v221, v2, v12, 32 bitop3:0x36
	v_bitop3_b32 v222, v2, v12, 64 bitop3:0x36
	v_bitop3_b32 v223, v2, v12, s77 bitop3:0x36
	v_add_u32_e32 v1, s22, v2
	v_and_or_b32 v2, v18, s6, v6
	s_add_i32 s6, s11, 0x1ec5
	v_lshlrev_b32_e32 v193, 2, v183
	v_add3_u32 v225, v7, 0, v2
	v_add_u32_e32 v2, s6, v191
	v_sub_u32_e32 v2, v2, v193
	v_mov_b32_e32 v16, v3
	v_mov_b32_e32 v17, v3
	s_add_i32 s16, s11, s2
	v_lshl_add_u64 v[186:187], s[8:9], 0, v[4:5]
	v_lshl_add_u64 v[188:189], s[24:25], 0, v[12:13]
	v_subrev_u32_e32 v226, s12, v2
	v_add_u32_e32 v227, 64, v8
	v_and_b32_e32 v230, 15, v0
	v_bfe_u32 v231, v0, 4, 3
	v_xor_b32_e32 v232, v230, v231
	v_sub_u32_e32 v232, v232, v230
	v_lshlrev_b32_e32 v232, 4, v232
	v_ashrrev_i32_e32 v233, 31, v232
	v_lshl_add_u64 v[184:185], v[184:185], 0, v[232:233]
	v_and_b32_e32 v234, 7, v0
	v_bfe_u32 v235, v0, 3, 3
	v_xor_b32_e32 v236, v234, v235
	v_sub_u32_e32 v236, v236, v234
	v_lshlrev_b32_e32 v236, 4, v236
	v_ashrrev_i32_e32 v237, 31, v236
	v_lshl_add_u64 v[188:189], v[188:189], 0, v[236:237]
	v_lshrrev_b32_e32 v234, 7, v0
	v_bfe_u32 v235, v0, 2, 3
	v_lshl_or_b32 v234, v234, 3, v235
	v_and_b32_e32 v236, 4, v234
	v_lshlrev_b32_e32 v236, 1, v236
	v_and_b32_e32 v237, 8, v234
	v_lshrrev_b32_e32 v237, 1, v237
	v_and_b32_e32 v234, 0x33, v234
	v_or3_b32 v234, v234, v236, v237
	v_lshrrev_b32_e32 v235, 4, v0
	v_sub_u32_e32 v234, v234, v235
	v_lshlrev_b32_e32 v234, 8, v234
	v_bfe_u32 v235, v0, 5, 2
	v_lshlrev_b32_e32 v235, 6, v235
	v_and_b32_e32 v236, 3, v0
	v_lshl_or_b32 v235, v236, 4, v235
	v_lshlrev_b32_e32 v236, 4, v230
	v_sub_u32_e32 v235, v235, v236
	v_add_u32_e32 v234, v234, v235
	v_ashrrev_i32_e32 v235, 31, v234
	v_lshl_add_u64 v[186:187], v[186:187], 0, v[234:235]
	v_mov_b32_e32 v2, v3
	v_mov_b32_e32 v4, v3
	v_mov_b32_e32 v6, v3
	v_mov_b32_e32 v7, v3
	v_mov_b32_e32 v8, v3
	v_mov_b32_e32 v9, v3
	v_mov_b32_e32 v10, v3
	v_mov_b32_e32 v11, v3
	v_mov_b32_e32 v12, v3
	v_mov_b32_e32 v14, v3
	v_mov_b32_e32 v15, v3
	v_mov_b64_e32 v[32:33], v[16:17]
	v_mov_b64_e32 v[48:49], v[16:17]
	v_mov_b64_e32 v[64:65], v[16:17]
	v_mov_b64_e32 v[80:81], v[16:17]
	s_or_b32 s17, s16, 31
	v_lshl_add_u32 v209, v191, 8, 0
	v_lshl_add_u32 v224, v191, 7, s0
	v_cmp_gt_u32_e64 s[0:1], 32, v192
	v_lshl_add_u32 v206, v191, 2, s22
	s_mov_b32 s22, 0
	v_mov_b32_e32 v229, 0
	v_mov_b32_e32 v228, 0xf149f2ca
	v_mov_b64_e32 v[30:31], v[14:15]
	v_mov_b64_e32 v[28:29], v[12:13]
	v_mov_b64_e32 v[26:27], v[10:11]
	v_mov_b64_e32 v[24:25], v[8:9]
	v_mov_b64_e32 v[22:23], v[6:7]
	v_mov_b64_e32 v[20:21], v[4:5]
	v_mov_b64_e32 v[18:19], v[2:3]
	v_mov_b64_e32 v[46:47], v[14:15]
	v_mov_b64_e32 v[44:45], v[12:13]
	v_mov_b64_e32 v[42:43], v[10:11]
	v_mov_b64_e32 v[40:41], v[8:9]
	v_mov_b64_e32 v[38:39], v[6:7]
	v_mov_b64_e32 v[36:37], v[4:5]
	v_mov_b64_e32 v[34:35], v[2:3]
	v_mov_b64_e32 v[62:63], v[14:15]
	v_mov_b64_e32 v[60:61], v[12:13]
	v_mov_b64_e32 v[58:59], v[10:11]
	v_mov_b64_e32 v[56:57], v[8:9]
	v_mov_b64_e32 v[54:55], v[6:7]
	v_mov_b64_e32 v[52:53], v[4:5]
	v_mov_b64_e32 v[50:51], v[2:3]
	v_mov_b64_e32 v[78:79], v[14:15]
	v_mov_b64_e32 v[76:77], v[12:13]
	v_mov_b64_e32 v[74:75], v[10:11]
	v_mov_b64_e32 v[72:73], v[8:9]
	v_mov_b64_e32 v[70:71], v[6:7]
	v_mov_b64_e32 v[68:69], v[4:5]
	v_mov_b64_e32 v[66:67], v[2:3]
	s_mov_b32 s23, 0
	s_waitcnt vmcnt(12)
	ds_write_b128 v208, v[178:181]
	s_waitcnt lgkmcnt(0)
	s_barrier
	s_branch .LBB0_4972

; template <int KIND>
; __device__ __forceinline__ void run_unit(LAS char* lds, const UnitArgs& U, int tid_in) {
;     ...
;         if (t + 1 < NT) FA_LOADT(U.j_lo + t + 1);
.LBB0_4974:
	s_and_b32 s8, s23, 1
	v_mov_b32_e32 v4, s8
	s_cmp_gt_i32 s22, s17
	s_cbranch_scc1 .Lmla_skipq
	v_lshlrev_b32_e32 v2, 14, v4
	v_add_u32_e32 v5, v209, v2
	v_add_u32_e32 v214, v5, v220
	v_add_u32_e32 v248, v5, v221
	ds_read_b128 v[6:9], v214 offset:32768
	ds_read_b128 v[10:13], v214 offset:40960
	ds_read_b128 v[14:17], v248 offset:32768
	ds_read_b128 v[230:233], v248 offset:40960
	v_add_u32_e32 v249, v5, v222
	v_add_u32_e32 v5, v5, v223
	ds_read_b128 v[234:237], v249 offset:32768
	ds_read_b128 v[240:243], v249 offset:40960
	ds_read_b128 v[244:247], v5 offset:32768
	ds_read_b128 v[194:197], v5 offset:40960
	s_and_b64 vcc, exec, s[6:7]
	s_cbranch_vccz .Lmla_q_nold
	v_readfirstlane_b32 s9, v0
	s_add_i32 s8, s23, 1
	s_and_b32 s8, s8, 1
	s_lshr_b32 s9, s9, 6
	s_lshl_b32 s9, s9, 10
	s_lshl_b32 vcc_lo, s8, 14
	s_add_i32 vcc_lo, vcc_lo, s9
	s_lshl_b32 s8, s8, 13
	s_add_i32 s8, s8, s9
	s_add_i32 s8, s8, 0x10000
	v_add_u32_e32 v98, s22, v182
	v_add_u32_e32 v100, 64, v98
	v_ashrrev_i32_e32 v101, 31, v100
	v_add_u32_e32 v104, 0x60, v98
	v_lshlrev_b64 v[100:101], 8, v[100:101]
	v_ashrrev_i32_e32 v105, 31, v104
	s_add_i32 m0, vcc_lo, 0x8000
	v_lshl_add_u64 v[102:103], v[184:185], 0, v[100:101]
	v_lshlrev_b64 v[104:105], 8, v[104:105]
	global_load_lds_dwordx4 v[102:103], off
	s_add_i32 m0, vcc_lo, 0xa000
	v_lshl_add_u64 v[106:107], v[184:185], 0, v[104:105]
	v_lshl_add_u64 v[100:101], v[186:187], 0, v[100:101]
	global_load_lds_dwordx4 v[106:107], off
	s_mov_b32 m0, vcc_lo
	v_lshl_add_u64 v[102:103], v[186:187], 0, v[104:105]
	v_add_u32_e32 v104, s22, v227
	global_load_lds_dwordx4 v[100:101], off
	s_add_i32 m0, vcc_lo, 0x2000
	v_ashrrev_i32_e32 v105, 31, v104
	v_lshlrev_b64 v[104:105], 7, v[104:105]
	global_load_lds_dwordx4 v[102:103], off
	s_mov_b32 m0, s8
	v_lshl_add_u64 v[104:105], v[188:189], 0, v[104:105]
	global_load_lds_dwordx4 v[104:105], off

; #define FA_SBAR() __builtin_amdgcn_sched_barrier(0)
; #define FA_WRITET(bf) do { *(LAS half8*)(lds + OFF_K + (bf) * SHM_K + kws) = st_k0; *(LAS half8*)(lds + OFF_K + (bf) * SHM_K + kws + 32 * 256) = st_k1; \
;         *(LAS half8*)(lds + OFF_V + (bf) * SHM_V + vst0) = st_v0; *(LAS half8*)(lds + OFF_V + (bf) * SHM_V + vst1) = st_v1; \
;         if constexpr (MLA) *(LAS half8*)(lds + OFF_KR + (bf) * SHM_KR + krw) = st_kr; } while (0)
; template <int KIND>
; __device__ __forceinline__ void run_unit(LAS char* lds, const UnitArgs& U, int tid_in) {
;     ...
;     for (int t = 0; t < NT; ++t) {
;         if (t + 1 < NT) FA_LOADT(U.j_lo + t + 1);
;         FA_SBAR();
;         FA_STEP(t);
;         FA_SBAR();
;         if (t + 1 < NT) { asm volatile("s_waitcnt vmcnt(0)" ::: "memory"); FA_WRITET((t + 1) & 1); dm_lo = dn_lo; dm_hi = dn_hi; }
;         __syncthreads();
.LBB0_4982:
	s_add_i32 s23, s23, 1
	s_waitcnt vmcnt(0)
	s_branch .LBB0_4971
.Lmla_skipq:
	s_and_b64 vcc, exec, s[6:7]
	s_cbranch_vccz .LBB0_4982
	v_readfirstlane_b32 s9, v0
	s_add_i32 s8, s23, 1
	s_and_b32 s8, s8, 1
	s_lshr_b32 s9, s9, 6
	s_lshl_b32 s9, s9, 10
	s_lshl_b32 vcc_lo, s8, 14
	s_add_i32 vcc_lo, vcc_lo, s9
	s_lshl_b32 s8, s8, 13
	s_add_i32 s8, s8, s9
	s_add_i32 s8, s8, 0x10000
	v_add_u32_e32 v2, s22, v182
	v_add_u32_e32 v4, 64, v2
	v_ashrrev_i32_e32 v5, 31, v4
	v_add_u32_e32 v8, 0x60, v2
	v_lshlrev_b64 v[4:5], 8, v[4:5]
	v_ashrrev_i32_e32 v9, 31, v8
	s_add_i32 m0, vcc_lo, 0x8000
	v_lshl_add_u64 v[6:7], v[184:185], 0, v[4:5]
	v_lshlrev_b64 v[8:9], 8, v[8:9]
	global_load_lds_dwordx4 v[6:7], off
	s_add_i32 m0, vcc_lo, 0xa000
	v_lshl_add_u64 v[10:11], v[184:185], 0, v[8:9]
	v_lshl_add_u64 v[4:5], v[186:187], 0, v[4:5]
	global_load_lds_dwordx4 v[10:11], off
	s_mov_b32 m0, vcc_lo
	v_lshl_add_u64 v[6:7], v[186:187], 0, v[8:9]
	v_add_u32_e32 v8, s22, v227
	global_load_lds_dwordx4 v[4:5], off
	s_add_i32 m0, vcc_lo, 0x2000
	v_ashrrev_i32_e32 v9, 31, v8
	v_lshlrev_b64 v[8:9], 7, v[8:9]
	global_load_lds_dwordx4 v[6:7], off
	s_mov_b32 m0, s8
	v_lshl_add_u64 v[8:9], v[188:189], 0, v[8:9]
	global_load_lds_dwordx4 v[8:9], off
	s_branch .LBB0_4982
